# stack: t1 + in-proj rstd prefetch + attention epilogue gate-load hoist + P1-end L2 writeback only on the forget-logit producers
# speedup vs baseline: 1.0052x; 1.0052x over previous
.LBB0_317:
	s_cmp_gt_i32 s71, 2
	s_cselect_b64 s[0:1], -1, 0
	s_and_b64 s[2:3], s[34:35], s[0:1]
	s_andn2_b64 vcc, exec, s[2:3]
	s_cbranch_vccnz .LBB0_371
	s_waitcnt vmcnt(0)
	s_barrier
	v_cmp_eq_u32_e32 vcc, 0, v161
	s_and_saveexec_b64 s[2:3], vcc
	s_cbranch_execz .Lsyn_pub_done
	s_cmpk_lg_i32 s92, 0x100
	s_cbranch_scc1 .Lsyn_dowb
	s_and_b32 s4, s76, 0xc0
	s_cmp_lg_u32 s4, 0x40
	s_cbranch_scc1 .Lsyn_nowb
.Lsyn_dowb:
	buffer_wbl2 sc1
	s_waitcnt vmcnt(0)
.Lsyn_nowb:
	v_mov_b32_e32 v0, 0x3900
	v_mov_b32_e32 v1, 1
	global_atomic_add v0, v1, s[72:73]
